# P9 LN2 row rebalance: waves owning a 65th-panel row drop two main rows, redistributed one each to 512 other waves
# baseline (speedup 1.0000x reference)
.LBB0_1224:
	s_or_b64 exec, exec, s[0:1]
	s_waitcnt lgkmcnt(0)
	s_barrier
	s_mov_b64 s[4:5], exec
	v_readlane_b32 s0, v250, 45
	v_readlane_b32 s1, v250, 46
	s_and_b64 s[0:1], s[4:5], s[0:1]
	s_mov_b64 exec, s[0:1]
	s_cbranch_execz .LBB0_1241
	v_mov_b32_e32 v9, 0
	v_mbcnt_hi_u32_b32 v24, -1, v225
	v_mov_b32_e32 v10, v178
	v_mov_b32_e32 v11, v9
	v_and_b32_e32 v0, 64, v24
	v_lshl_add_u64 v[12:13], s[82:83], 0, v[10:11]
	v_lshl_add_u64 v[14:15], s[88:89], 0, v[10:11]
	s_mov_b64 s[6:7], 0
	s_movk_i32 s15, 0x4000
	s_mov_b32 s16, 0xfe03f81
	v_add_u32_e32 v25, 64, v0
	v_xor_b32_e32 v26, 1, v24
	v_xor_b32_e32 v27, 2, v24
	v_xor_b32_e32 v28, 4, v24
	v_xor_b32_e32 v29, 8, v24
	v_xor_b32_e32 v30, 16, v24
	v_xor_b32_e32 v31, 32, v24
	v_mov_b32_e32 v32, 0x3727c5ac
	s_mov_b32 s17, 0xf800000
	v_mov_b32_e32 v33, 0x260
	s_movk_i32 s18, 0x3fff
	v_mov_b32_e32 v190, 0x3fff
	v_mov_b32_e32 v191, -1
	v_mov_b32_e32 v192, 0x4000
	v_mov_b32_e32 v193, 0x4000
	s_cmpk_lg_i32 s94, 0x100
	s_cbranch_scc1 .Lp9_nobal
	v_mov_b32_e32 v194, 0x2fff
	v_cmp_gt_u32_e32 vcc, 0x100, v188
	s_nop 1
	v_cndmask_b32_e32 v190, v190, v194, vcc
	v_add_u32_e32 v194, 0x3700, v188
	v_subrev_u32_e32 v195, 0x100, v188
	v_cmp_gt_u32_e32 vcc, 0x100, v195
	s_nop 1
	v_cndmask_b32_e32 v191, v191, v194, vcc
	v_add_u32_e32 v194, 0x2e00, v188
	v_subrev_u32_e32 v195, 0x200, v188
	v_cmp_gt_u32_e32 vcc, 0x100, v195
	s_nop 1
	v_cndmask_b32_e32 v191, v191, v194, vcc
	v_cndmask_b32_e64 v193, v193, 0, vcc
.Lp9_nobal:
	s_branch .LBB0_1227
.LBB0_1226:
	s_or_b64 exec, exec, s[0:1]
	v_add_u32_e32 v188, s64, v16
	v_cmp_gt_i32_e32 vcc, v188, v190
	v_cmp_le_i32_e64 s[20:21], 0, v191
	s_nop 1
	s_and_b64 s[20:21], s[20:21], vcc
	s_nop 1
	v_cndmask_b32_e64 v188, v188, v191, s[20:21]
	v_cndmask_b32_e64 v192, v192, v193, s[20:21]
	v_cndmask_b32_e64 v191, v191, -1, s[20:21]
	s_andn2_b64 vcc, vcc, s[20:21]
	s_or_b64 s[6:7], vcc, s[6:7]
	s_andn2_b64 exec, exec, s[6:7]
	s_cbranch_execz .LBB0_1241
.LBB0_1227:
	v_add_u32_e32 v16, s64, v188
	v_cmp_gt_i32_e32 vcc, v192, v16
	v_mov_b64_e32 v[18:19], 0
	s_and_saveexec_b64 s[0:1], vcc
	s_cbranch_execz .LBB0_1229
	v_mul_hi_i32 v0, v16, s16
	v_lshrrev_b32_e32 v1, 31, v0
	v_ashrrev_i32_e32 v0, 7, v0
	v_add_u32_e32 v0, v0, v1
	v_mul_i32_i24_e32 v1, 0xfffff7f0, v0
	v_add3_u32 v4, s64, v1, v188
	v_ashrrev_i32_e32 v1, 31, v0
	v_add_u32_e32 v8, -16, v4
	v_lshlrev_b64 v[0:1], 23, v[0:1]
	v_lshl_add_u64 v[0:1], s[90:91], 0, v[0:1]
	v_lshlrev_b64 v[2:3], 12, v[8:9]
	v_lshl_add_u64 v[0:1], v[0:1], 0, v[2:3]
	v_cmp_lt_i32_e32 vcc, 15, v4
	s_nop 1
	v_cndmask_b32_e32 v19, 0, v1, vcc
	v_cndmask_b32_e32 v18, 0, v0, vcc
